# P8 (QKV head-major) epilogue: column remap so each wave owns one head's 128B row; half-line stores adjacent
# baseline (speedup 1.0000x reference)
.LBB0_41:
	s_lshl_b32 s26, s4, 1
	s_lshl_b32 s27, s24, 1
	v_mov_b32_e32 v55, v5
	v_or_b32_e32 v54, s26, v11
	v_or_b32_e32 v4, s27, v52
	s_add_i32 s64, s26, 4
	s_add_i32 s65, s27, 4
	v_mov_b32_e32 v57, v5
	s_add_i32 s66, s26, 8
	s_add_i32 s67, s27, 8
	v_lshl_add_u64 v[82:83], v[4:5], 2, s[12:13]
	v_lshl_add_u64 v[84:85], v[54:55], 2, s[12:13]
	v_mad_u64_u32 v[86:87], s[62:63], v4, s40, v[50:51]
	v_mad_u64_u32 v[54:55], s[62:63], v54, s40, v[50:51]
	v_or_b32_e32 v56, s64, v11
	v_or_b32_e32 v4, s65, v52
	v_mov_b32_e32 v59, v5
	s_add_i32 s68, s26, 12
	s_add_i32 s69, s27, 12
	v_or_b32_e32 v58, s66, v11
	global_load_dword v82, v[82:83], off
	s_nop 0
	global_load_dword v83, v[84:85], off
	s_nop 0
	global_load_dword v84, v[86:87], off
	global_load_dword v85, v[54:55], off
	v_lshl_add_u64 v[54:55], v[4:5], 2, s[12:13]
	v_lshl_add_u64 v[86:87], v[56:57], 2, s[12:13]
	v_mad_u64_u32 v[88:89], s[62:63], v4, s40, v[50:51]
	v_mad_u64_u32 v[56:57], s[62:63], v56, s40, v[50:51]
	v_or_b32_e32 v4, s67, v52
	v_mov_b32_e32 v61, v5
	s_add_i32 s70, s26, 16
	s_add_i32 s71, s27, 16
	v_or_b32_e32 v60, s68, v11
	v_lshl_add_u64 v[90:91], v[58:59], 2, s[12:13]
	v_mad_u64_u32 v[58:59], s[62:63], v58, s40, v[50:51]
	global_load_dword v54, v[54:55], off
	s_nop 0
	global_load_dword v55, v[86:87], off
	s_nop 0
	global_load_dword v86, v[88:89], off
	global_load_dword v87, v[56:57], off
	v_lshl_add_u64 v[56:57], v[4:5], 2, s[12:13]
	v_mad_u64_u32 v[88:89], s[62:63], v4, s40, v[50:51]
	v_or_b32_e32 v4, s69, v52
	v_mov_b32_e32 v63, v5
	s_add_i32 s72, s26, 20
	s_add_i32 s73, s27, 20
	v_or_b32_e32 v62, s70, v11
	v_lshl_add_u64 v[92:93], v[60:61], 2, s[12:13]
	v_mad_u64_u32 v[60:61], s[62:63], v60, s40, v[50:51]
	global_load_dword v56, v[56:57], off
	s_nop 0
	global_load_dword v57, v[90:91], off
	s_nop 0
	global_load_dword v88, v[88:89], off
	s_nop 0
	global_load_dword v89, v[58:59], off
	v_lshl_add_u64 v[58:59], v[4:5], 2, s[12:13]
	v_mad_u64_u32 v[90:91], s[62:63], v4, s40, v[50:51]
	v_or_b32_e32 v4, s71, v52
	v_mov_b32_e32 v65, v5
	s_add_i32 s74, s26, 24
	s_add_i32 s75, s27, 24
	v_or_b32_e32 v64, s72, v11
	v_lshl_add_u64 v[94:95], v[62:63], 2, s[12:13]
	v_mad_u64_u32 v[62:63], s[62:63], v62, s40, v[50:51]
	global_load_dword v58, v[58:59], off
	s_nop 0
	global_load_dword v59, v[92:93], off
	s_nop 0
	global_load_dword v90, v[90:91], off
	s_nop 0
	global_load_dword v91, v[60:61], off
	v_lshl_add_u64 v[60:61], v[4:5], 2, s[12:13]
	v_mad_u64_u32 v[92:93], s[62:63], v4, s40, v[50:51]
	v_or_b32_e32 v4, s73, v52
	v_mov_b32_e32 v67, v5
	s_add_i32 s83, s27, 28
	v_or_b32_e32 v66, s74, v11
	v_lshl_add_u64 v[96:97], v[64:65], 2, s[12:13]
	v_mad_u64_u32 v[64:65], s[62:63], v64, s40, v[50:51]
	global_load_dword v60, v[60:61], off
	s_nop 0
	global_load_dword v61, v[94:95], off
	s_nop 0
	global_load_dword v92, v[92:93], off
	s_nop 0
	global_load_dword v93, v[62:63], off
	v_lshl_add_u64 v[62:63], v[4:5], 2, s[12:13]
	v_mad_u64_u32 v[94:95], s[62:63], v4, s40, v[50:51]
	v_or_b32_e32 v4, s75, v52
	s_add_i32 s82, s26, 28
	v_lshl_add_u64 v[98:99], v[66:67], 2, s[12:13]
	v_mad_u64_u32 v[66:67], s[62:63], v66, s40, v[50:51]
	global_load_dword v62, v[62:63], off
	s_nop 0
	global_load_dword v63, v[96:97], off
	s_nop 0
	global_load_dword v94, v[94:95], off
	s_nop 0
	global_load_dword v95, v[64:65], off
	v_lshl_add_u64 v[64:65], v[4:5], 2, s[12:13]
	v_mad_u64_u32 v[96:97], s[62:63], v4, s40, v[50:51]
	v_or_b32_e32 v4, s83, v52
	v_mov_b32_e32 v69, v5
	v_or_b32_e32 v68, s82, v11
	global_load_dword v64, v[64:65], off
	s_nop 0
	global_load_dword v65, v[98:99], off
	s_nop 0
	global_load_dword v96, v[96:97], off
	s_nop 0
	global_load_dword v97, v[66:67], off
	v_lshl_add_u64 v[66:67], v[4:5], 2, s[12:13]
	v_mad_u64_u32 v[98:99], s[62:63], v4, s40, v[50:51]
	v_lshl_add_u64 v[100:101], v[68:69], 2, s[12:13]
	v_mad_u64_u32 v[68:69], s[62:63], v68, s40, v[50:51]
	global_load_dword v66, v[66:67], off
	s_nop 0
	global_load_dword v67, v[100:101], off
	s_nop 0
	global_load_dword v98, v[98:99], off
	s_nop 0
	global_load_dword v99, v[68:69], off
	v_or_b32_e32 v4, s26, v1
	v_or_b32_e32 v53, s27, v2
	v_mad_u64_u32 v[68:69], s[26:27], v53, s3, v[10:11]
	v_mad_u64_u32 v[100:101], s[26:27], v4, s3, v[10:11]
	v_or_b32_e32 v53, s65, v2
	v_or_b32_e32 v4, s64, v1
	v_or_b32_e32 v101, s67, v2
	v_mad_u64_u32 v[102:103], s[26:27], v53, s3, v[10:11]
	s_waitcnt vmcnt(28)
	v_pk_mul_f32 v[82:83], v[82:83], v[84:85]
	v_or_b32_e32 v69, s66, v1
	v_or_b32_e32 v110, s69, v2
	v_mad_u64_u32 v[104:105], s[26:27], v4, s3, v[10:11]
	v_mad_u64_u32 v[106:107], s[26:27], v101, s3, v[10:11]
	ds_write_b32 v68, v82
	ds_write_b32 v100, v83
	v_or_b32_e32 v112, s68, v1
	v_or_b32_e32 v114, s71, v2
	s_waitcnt vmcnt(24)
	v_pk_mul_f32 v[54:55], v[54:55], v[86:87]
	ds_write_b32 v102, v54
	ds_write_b32 v104, v55
	v_mad_u64_u32 v[108:109], s[26:27], v69, s3, v[10:11]
	v_mad_u64_u32 v[110:111], s[26:27], v110, s3, v[10:11]
	v_or_b32_e32 v116, s70, v1
	v_or_b32_e32 v118, s73, v2
	v_mad_u64_u32 v[112:113], s[26:27], v112, s3, v[10:11]
	v_mad_u64_u32 v[114:115], s[26:27], v114, s3, v[10:11]
	s_waitcnt vmcnt(20)
	v_pk_mul_f32 v[54:55], v[56:57], v[88:89]
	ds_write_b32 v106, v54
	ds_write_b32 v108, v55
	v_or_b32_e32 v120, s72, v1
	v_or_b32_e32 v122, s75, v2
	v_mad_u64_u32 v[116:117], s[26:27], v116, s3, v[10:11]
	v_mad_u64_u32 v[118:119], s[26:27], v118, s3, v[10:11]
	s_add_i32 s24, s24, 16
	s_add_i32 s4, s4, 16
	s_add_i32 s25, s25, -16
	v_or_b32_e32 v124, s74, v1
	s_waitcnt vmcnt(16)
	v_pk_mul_f32 v[54:55], v[58:59], v[90:91]
	ds_write_b32 v110, v54
	ds_write_b32 v112, v55
	v_or_b32_e32 v126, s83, v2
	v_mad_u64_u32 v[120:121], s[26:27], v120, s3, v[10:11]
	v_mad_u64_u32 v[122:123], s[26:27], v122, s3, v[10:11]
	v_or_b32_e32 v128, s82, v1
	s_cmp_lg_u32 s25, 0
	v_mad_u64_u32 v[124:125], s[26:27], v124, s3, v[10:11]
	s_waitcnt vmcnt(12)
	v_pk_mul_f32 v[54:55], v[60:61], v[92:93]
	ds_write_b32 v114, v54
	ds_write_b32 v116, v55
	v_mad_u64_u32 v[126:127], s[26:27], v126, s3, v[10:11]
	v_mad_u64_u32 v[128:129], s[26:27], v128, s3, v[10:11]
	s_waitcnt vmcnt(8)
	v_pk_mul_f32 v[54:55], v[62:63], v[94:95]
	ds_write_b32 v118, v54
	ds_write_b32 v120, v55
	s_waitcnt vmcnt(4)
	v_pk_mul_f32 v[54:55], v[64:65], v[96:97]
	ds_write_b32 v122, v54
	ds_write_b32 v124, v55
	s_waitcnt vmcnt(0)
	v_pk_mul_f32 v[54:55], v[66:67], v[98:99]
	ds_write_b32 v126, v54
	ds_write_b32 v128, v55
	s_cbranch_scc1 .LBB0_41
	s_waitcnt lgkmcnt(0)
	ds_read2_b32 v[50:51], v70 offset1:33
	s_and_b32 s1, 0xffff, s1
	s_and_b32 s0, 0xffff, s0
	s_waitcnt lgkmcnt(0)
	v_cvt_pk_bf16_f32 v50, v50, v51
	ds_read2_b32 v[52:53], v70 offset0:66 offset1:99
	s_lshl_b32 s4, s0, 1
	s_bfe_u32 s98, s1, 0x10005
	s_bfe_u32 s99, s1, 0x20006
	s_lshl_b32 s98, s98, 7
	s_lshl_b32 s99, s99, 5
	s_or_b32 s98, s98, s99
	s_andn2_b32 s99, s1, 0xe0
	s_or_b32 s98, s98, s99
	v_or_b32_e32 v4, s98, v45
	s_waitcnt lgkmcnt(0)
	v_cvt_pk_bf16_f32 v51, v52, v53
	ds_read2_b32 v[52:53], v70 offset0:132 offset1:165
	v_lshl_add_u64 v[56:57], v[26:27], 0, s[4:5]
	v_lshlrev_b32_e32 v4, 11, v4
	s_waitcnt lgkmcnt(0)
	v_cvt_pk_bf16_f32 v52, v52, v53
	ds_read2_b32 v[54:55], v70 offset0:198 offset1:231
	s_waitcnt lgkmcnt(0)
	v_cvt_pk_bf16_f32 v53, v54, v55
	v_lshl_add_u64 v[58:59], v[56:57], 0, v[4:5]
	ds_read2_b32 v[54:55], v70 offset0:8 offset1:41
	global_store_dwordx4 v[58:59], v[50:53], off
	v_or_b32_e32 v4, s98, v71
	v_lshlrev_b32_e32 v4, 11, v4
	s_waitcnt lgkmcnt(0)
	v_cvt_pk_bf16_f32 v50, v54, v55
	ds_read2_b32 v[52:53], v70 offset0:74 offset1:107
	s_waitcnt lgkmcnt(0)
	v_cvt_pk_bf16_f32 v51, v52, v53
	ds_read2_b32 v[52:53], v70 offset0:140 offset1:173
	s_waitcnt lgkmcnt(0)
	v_cvt_pk_bf16_f32 v52, v52, v53
	ds_read2_b32 v[54:55], v70 offset0:206 offset1:239
	s_waitcnt lgkmcnt(0)
	v_cvt_pk_bf16_f32 v53, v54, v55
	v_lshl_add_u64 v[58:59], v[56:57], 0, v[4:5]
	ds_read2_b32 v[54:55], v70 offset0:16 offset1:49
	global_store_dwordx4 v[58:59], v[50:53], off
	v_or_b32_e32 v4, s98, v72
	v_lshlrev_b32_e32 v4, 11, v4
	s_waitcnt lgkmcnt(0)
	v_cvt_pk_bf16_f32 v50, v54, v55
	ds_read2_b32 v[52:53], v70 offset0:82 offset1:115
	s_waitcnt lgkmcnt(0)
	v_cvt_pk_bf16_f32 v51, v52, v53
	ds_read2_b32 v[52:53], v70 offset0:148 offset1:181
	s_waitcnt lgkmcnt(0)
	v_cvt_pk_bf16_f32 v52, v52, v53
	ds_read2_b32 v[54:55], v70 offset0:214 offset1:247
	s_waitcnt lgkmcnt(0)
	v_cvt_pk_bf16_f32 v53, v54, v55
	v_lshl_add_u64 v[58:59], v[56:57], 0, v[4:5]
	ds_read2_b32 v[54:55], v70 offset0:24 offset1:57
	global_store_dwordx4 v[58:59], v[50:53], off
	v_or_b32_e32 v4, s98, v73
	v_lshlrev_b32_e32 v4, 11, v4
	s_waitcnt lgkmcnt(0)
	v_cvt_pk_bf16_f32 v50, v54, v55
	ds_read2_b32 v[52:53], v70 offset0:90 offset1:123
	s_waitcnt lgkmcnt(0)
	v_cvt_pk_bf16_f32 v51, v52, v53
	ds_read2_b32 v[52:53], v70 offset0:156 offset1:189
	s_waitcnt lgkmcnt(0)
	v_cvt_pk_bf16_f32 v52, v52, v53
	ds_read2_b32 v[54:55], v70 offset0:222 offset1:255
	s_waitcnt lgkmcnt(0)
	v_cvt_pk_bf16_f32 v53, v54, v55
	v_lshl_add_u64 v[54:55], v[56:57], 0, v[4:5]
	global_store_dwordx4 v[54:55], v[50:53], off
	s_waitcnt lgkmcnt(0)

.LBB0_930:
	s_lshl_b32 s20, s12, 5
	s_mov_b64 s[12:13], 0x80
	s_and_b32 s40, s20, 0x60
	s_add_i32 m0, s30, 0x18000
	v_lshl_add_u64 v[6:7], v[6:7], 0, s[12:13]
	s_lshl_b32 s15, s14, 13
	s_lshl_b32 s21, s40, 7
	s_ashr_i32 s41, s2, 31
	s_waitcnt vmcnt(2)
	s_barrier
	global_load_lds_dwordx4 v[6:7], off
	v_lshl_add_u64 v[4:5], v[4:5], 0, s[12:13]
	s_add_i32 m0, s30, 0x1a000
	s_add_i32 s42, s30, 0x8000
	s_add_i32 s43, s30, 0xa000
	global_load_lds_dwordx4 v[4:5], off
	v_lshl_add_u64 v[0:1], v[0:1], 0, s[12:13]
	s_mov_b32 m0, s42
	s_add_u32 s18, s34, 0x40080
	global_load_lds_dwordx4 v[0:1], off
	v_lshl_add_u64 v[0:1], v[2:3], 0, s[12:13]
	s_mov_b32 m0, s43
	s_addc_u32 s19, s35, 0
	global_load_lds_dwordx4 v[0:1], off
	s_add_i32 m0, s30, 0x1c000
	v_lshl_add_u64 v[0:1], s[18:19], 0, v[132:133]
	global_load_lds_dwordx4 v[0:1], off
	v_lshl_add_u64 v[0:1], s[18:19], 0, v[128:129]
	s_add_i32 m0, s30, 0x1e000
	s_sext_i32_i8 s5, s0
	global_load_lds_dwordx4 v[0:1], off
	v_bfe_u32 v0, v192, 4, 2
	v_and_b32_e32 v1, 15, v192
	v_lshlrev_b32_e32 v136, 4, v0
	v_lshl_or_b32 v150, s14, 6, v1
	v_lshlrev_b32_e32 v2, 3, v0
	v_lshl_or_b32 v0, v1, 6, v136
	v_lshlrev_b32_e32 v1, 2, v192
	v_and_b32_e32 v1, 32, v1
	v_bitop3_b32 v3, v0, s15, v1 bitop3:0xde
	v_lshlrev_b32_e32 v0, 6, v192
	s_movk_i32 s0, 0x3c0
	v_and_or_b32 v0, v0, s0, v136
	v_bitop3_b32 v151, s21, v0, v1 bitop3:0xf6
	s_cmpk_lt_u32 s1, 0x100
	v_lshl_add_u64 v[0:1], s[56:57], 0, v[136:137]
	s_mov_b64 s[0:1], 0x600000
	v_lshl_add_u64 v[138:139], v[0:1], 0, s[0:1]
	v_lshlrev_b32_e32 v1, 8, v192
	v_mov_b32_e32 v0, v2
	v_and_b32_e32 v1, 0x38000, v1
	v_lshlrev_b32_e32 v2, 11, v11
	v_or3_b32 v1, v9, v1, v2
	v_add_u32_e32 v140, v1, v10
	v_lshlrev_b32_e32 v1, 4, v8
	v_and_b32_e32 v1, 0x78000, v1
	s_waitcnt vmcnt(6)
	v_or3_b32 v1, v9, v1, v2
	s_cselect_b64 s[14:15], -1, 0
	v_add_u32_e32 v142, v1, v10
	s_add_i32 s46, 0, 0x10000
	s_add_i32 s47, 0, 0x14000
	v_mbcnt_lo_u32_b32 v1, -1, 0
	s_ashr_i32 s44, s60, 31
	s_mov_b32 s45, s60
	v_mov_b32_e32 v141, v137
	v_mov_b32_e32 v143, v137
	v_mov_b64_e32 v[144:145], 0x600
	v_mov_b64_e32 v[146:147], 0x5ff
	v_add_u32_e32 v152, s46, v151
	v_add_u32_e32 v153, s47, v151
	v_add_u32_e32 v154, 0, v3
	v_mbcnt_hi_u32_b32 v155, -1, v1
	v_mov_b32_e32 v156, 0x358637bd
	s_mov_b32 s48, 0xf800000
	v_mov_b32_e32 v157, 0x260
	v_lshlrev_b32_e32 v136, 1, v0
	s_mov_b32 s49, 64
	v_mov_b32_e32 v158, 0x3e38aa3b
	s_barrier
	s_branch .LBB0_933

.LBB0_939:
	v_lshl_add_u32 v148, s4, 8, v150
	v_ashrrev_i32_e32 v149, 31, v148
	v_lshlrev_b64 v[160:161], 6, v[148:149]
	v_lshl_add_u64 v[160:161], v[138:139], 0, v[160:161]
	global_load_dwordx4 v[160:163], v[160:161], off
	v_and_b32_e32 v164, 64, v155
	v_xor_b32_e32 v159, 16, v155
	v_add_u32_e32 v166, 64, v164
	v_cmp_lt_i32_e32 vcc, v159, v166
	v_xor_b32_e32 v165, 32, v155
	s_lshl_b32 s4, s5, 8
	v_cndmask_b32_e32 v159, v155, v159, vcc
	v_lshlrev_b32_e32 v159, 2, v159
	v_cmp_lt_i32_e32 vcc, v165, v166
	s_lshl_b32 s98, s40, 1
	s_or_b32 s4, s4, s98
	s_cmp_lt_i32 s5, 4
	v_cndmask_b32_e32 v170, v155, v165, vcc
	s_cselect_b64 vcc, -1, 0
	v_lshlrev_b64 v[166:167], 7, v[148:149]
	v_cndmask_b32_e32 v149, 1.0, v158, vcc
	s_ashr_i32 s4, s4, 6
	s_ashr_i32 s5, s4, 31
	s_lshl_b64 s[4:5], s[4:5], 22
	s_add_u32 s26, s10, s4
	s_addc_u32 s27, s11, s5
	v_lshl_add_u64 v[166:167], s[26:27], 0, v[166:167]
	v_lshl_add_u64 v[166:167], v[166:167], 0, v[136:137]
	v_or_b32_e32 v164, 16, v148
	v_ashrrev_i32_e32 v165, 31, v164
	s_waitcnt vmcnt(0)
	v_mov_b32_e32 v168, v161
	v_mov_b32_e32 v169, v162
	v_mov_b32_e32 v161, v163
	v_pk_add_f32 v[160:161], v[168:169], v[160:161]
	v_lshlrev_b64 v[162:163], 6, v[164:165]
	v_add_f32_e32 v161, v160, v161
	ds_bpermute_b32 v168, v159, v161
	v_lshlrev_b32_e32 v160, 2, v170
	v_lshl_add_u64 v[162:163], v[138:139], 0, v[162:163]
	s_waitcnt lgkmcnt(0)
	v_add_f32_e32 v161, v161, v168
	ds_bpermute_b32 v168, v160, v161
	s_waitcnt lgkmcnt(0)
	v_add_f32_e32 v161, v161, v168
	v_fmamk_f32 v161, v161, 0x3a800000, v156
	v_add_co_u32_e32 v168, vcc, s49, v166
	s_nop 1
	v_addc_co_u32_e32 v169, vcc, 0, v167, vcc
	v_rsq_f32_e32 v174, v161
	v_mul_f32_e32 v173, 0.5, v161
	v_mul_f32_e32 v161, v174, v174
	v_fma_f32 v173, -v173, v161, 0.5
	v_fma_f32 v161, v174, v173, v174
	v_mul_f32_e32 v170, v149, v161
	v_pk_mul_f32 v[126:127], v[126:127], v[170:171] op_sel_hi:[1,0]
	v_pk_mul_f32 v[124:125], v[124:125], v[170:171] op_sel_hi:[1,0]
	v_pk_mul_f32 v[122:123], v[122:123], v[170:171] op_sel_hi:[1,0]
	v_pk_mul_f32 v[120:121], v[120:121], v[170:171] op_sel_hi:[1,0]
	v_pk_mul_f32 v[118:119], v[118:119], v[170:171] op_sel_hi:[1,0]
	v_pk_mul_f32 v[116:117], v[116:117], v[170:171] op_sel_hi:[1,0]
	v_pk_mul_f32 v[172:173], v[114:115], v[170:171] op_sel_hi:[1,0]
	v_pk_mul_f32 v[170:171], v[112:113], v[170:171] op_sel_hi:[1,0]
	v_cvt_pk_bf16_f32 v112, v124, v125
	v_cvt_pk_bf16_f32 v113, v126, v127
	v_cvt_pk_bf16_f32 v114, v120, v121
	v_cvt_pk_bf16_f32 v115, v122, v123
	global_store_dwordx4 v[166:167], v[112:115], off
	s_nop 1
	v_cvt_pk_bf16_f32 v112, v116, v117
	v_cvt_pk_bf16_f32 v113, v118, v119
	v_cvt_pk_bf16_f32 v114, v170, v171
	v_cvt_pk_bf16_f32 v115, v172, v173
	global_store_dwordx4 v[168:169], v[112:115], off
	global_load_dwordx4 v[112:115], v[162:163], off
	s_waitcnt vmcnt(0)
	v_mov_b32_e32 v116, v113
	v_mov_b32_e32 v117, v114
	v_mov_b32_e32 v113, v115
	v_pk_add_f32 v[112:113], v[116:117], v[112:113]
	v_lshlrev_b64 v[114:115], 7, v[164:165]
	v_add_f32_e32 v112, v112, v113
	ds_bpermute_b32 v113, v159, v112
	v_lshl_add_u64 v[114:115], s[26:27], 0, v[114:115]
	v_lshl_add_u64 v[114:115], v[114:115], 0, v[136:137]
	s_waitcnt lgkmcnt(0)
	v_add_f32_e32 v118, v112, v113
	ds_bpermute_b32 v119, v160, v118
	v_or_b32_e32 v112, 32, v148
	v_ashrrev_i32_e32 v113, 31, v112
	v_lshlrev_b64 v[116:117], 6, v[112:113]
	v_lshl_add_u64 v[116:117], v[138:139], 0, v[116:117]
	s_waitcnt lgkmcnt(0)
	v_add_f32_e32 v118, v118, v119
	v_fmamk_f32 v118, v118, 0x3a800000, v156
	v_mov_b32_e32 v120, v118
	v_add_co_u32_e32 v118, vcc, s49, v114
	s_nop 1
	v_addc_co_u32_e32 v119, vcc, 0, v115, vcc
	v_rsq_f32_e32 v125, v120
	v_mul_f32_e32 v124, 0.5, v120
	v_mul_f32_e32 v120, v125, v125
	v_fma_f32 v124, -v124, v120, 0.5
	v_fma_f32 v120, v125, v124, v125
	v_mul_f32_e32 v120, v149, v120
	v_pk_mul_f32 v[110:111], v[110:111], v[120:121] op_sel_hi:[1,0]
	v_pk_mul_f32 v[108:109], v[108:109], v[120:121] op_sel_hi:[1,0]
	v_pk_mul_f32 v[106:107], v[106:107], v[120:121] op_sel_hi:[1,0]
	v_pk_mul_f32 v[104:105], v[104:105], v[120:121] op_sel_hi:[1,0]
	v_pk_mul_f32 v[102:103], v[102:103], v[120:121] op_sel_hi:[1,0]
	v_pk_mul_f32 v[100:101], v[100:101], v[120:121] op_sel_hi:[1,0]
	v_pk_mul_f32 v[122:123], v[98:99], v[120:121] op_sel_hi:[1,0]
	v_pk_mul_f32 v[120:121], v[96:97], v[120:121] op_sel_hi:[1,0]
	v_cvt_pk_bf16_f32 v96, v108, v109
	v_cvt_pk_bf16_f32 v97, v110, v111
	v_cvt_pk_bf16_f32 v98, v104, v105
	v_cvt_pk_bf16_f32 v99, v106, v107
	global_store_dwordx4 v[114:115], v[96:99], off
	s_nop 1
	v_cvt_pk_bf16_f32 v96, v100, v101
	v_cvt_pk_bf16_f32 v97, v102, v103
	v_cvt_pk_bf16_f32 v98, v120, v121
	v_cvt_pk_bf16_f32 v99, v122, v123
	global_store_dwordx4 v[118:119], v[96:99], off
	global_load_dwordx4 v[96:99], v[116:117], off
	s_waitcnt vmcnt(0)
	v_mov_b32_e32 v100, v97
	v_mov_b32_e32 v101, v98
	v_mov_b32_e32 v97, v99
	v_pk_add_f32 v[96:97], v[100:101], v[96:97]
	v_lshlrev_b64 v[98:99], 7, v[112:113]
	v_add_f32_e32 v96, v96, v97
	ds_bpermute_b32 v97, v159, v96
	v_lshl_add_u64 v[98:99], s[26:27], 0, v[98:99]
	v_lshl_add_u64 v[98:99], v[98:99], 0, v[136:137]
	s_waitcnt lgkmcnt(0)
	v_add_f32_e32 v102, v96, v97
	ds_bpermute_b32 v103, v160, v102
	v_or_b32_e32 v96, 48, v148
	v_ashrrev_i32_e32 v97, 31, v96
	v_lshlrev_b64 v[100:101], 6, v[96:97]
	v_lshl_add_u64 v[100:101], v[138:139], 0, v[100:101]
	s_waitcnt lgkmcnt(0)
	v_add_f32_e32 v102, v102, v103
	v_fmamk_f32 v102, v102, 0x3a800000, v156
	v_mov_b32_e32 v104, v102
	v_add_co_u32_e32 v102, vcc, s49, v98
	s_nop 1
	v_addc_co_u32_e32 v103, vcc, 0, v99, vcc
	v_rsq_f32_e32 v109, v104
	v_mul_f32_e32 v108, 0.5, v104
	v_mul_f32_e32 v104, v109, v109
	v_fma_f32 v108, -v108, v104, 0.5
	v_fma_f32 v104, v109, v108, v109
	v_mul_f32_e32 v104, v149, v104
	v_pk_mul_f32 v[94:95], v[94:95], v[104:105] op_sel_hi:[1,0]
	v_pk_mul_f32 v[92:93], v[92:93], v[104:105] op_sel_hi:[1,0]
	v_pk_mul_f32 v[90:91], v[90:91], v[104:105] op_sel_hi:[1,0]
	v_pk_mul_f32 v[88:89], v[88:89], v[104:105] op_sel_hi:[1,0]
	v_pk_mul_f32 v[86:87], v[86:87], v[104:105] op_sel_hi:[1,0]
	v_pk_mul_f32 v[84:85], v[84:85], v[104:105] op_sel_hi:[1,0]
	v_pk_mul_f32 v[106:107], v[82:83], v[104:105] op_sel_hi:[1,0]
	v_pk_mul_f32 v[104:105], v[80:81], v[104:105] op_sel_hi:[1,0]
	v_cvt_pk_bf16_f32 v80, v92, v93
	v_cvt_pk_bf16_f32 v81, v94, v95
	v_cvt_pk_bf16_f32 v82, v88, v89
	v_cvt_pk_bf16_f32 v83, v90, v91
	global_store_dwordx4 v[98:99], v[80:83], off
	s_nop 1
	v_cvt_pk_bf16_f32 v80, v84, v85
	v_cvt_pk_bf16_f32 v81, v86, v87
	v_cvt_pk_bf16_f32 v82, v104, v105
	v_cvt_pk_bf16_f32 v83, v106, v107
	global_store_dwordx4 v[102:103], v[80:83], off
	global_load_dwordx4 v[80:83], v[100:101], off
	s_waitcnt vmcnt(0)
	v_mov_b32_e32 v84, v81
	v_mov_b32_e32 v85, v82
	v_mov_b32_e32 v81, v83
	v_pk_add_f32 v[80:81], v[84:85], v[80:81]
	v_lshlrev_b64 v[82:83], 7, v[96:97]
	v_add_f32_e32 v80, v80, v81
	ds_bpermute_b32 v81, v159, v80
	v_lshl_add_u64 v[82:83], s[26:27], 0, v[82:83]
	v_lshl_add_u64 v[82:83], v[82:83], 0, v[136:137]
	s_waitcnt lgkmcnt(0)
	v_add_f32_e32 v86, v80, v81
	ds_bpermute_b32 v87, v160, v86
	v_add_u32_e32 v80, 0x80, v148
	v_ashrrev_i32_e32 v81, 31, v80
	v_lshlrev_b64 v[84:85], 6, v[80:81]
	v_lshl_add_u64 v[84:85], v[138:139], 0, v[84:85]
	s_waitcnt lgkmcnt(0)
	v_add_f32_e32 v86, v86, v87
	v_fmamk_f32 v86, v86, 0x3a800000, v156
	v_mov_b32_e32 v88, v86
	v_add_co_u32_e32 v86, vcc, s49, v82
	s_nop 1
	v_addc_co_u32_e32 v87, vcc, 0, v83, vcc
	v_rsq_f32_e32 v93, v88
	v_mul_f32_e32 v92, 0.5, v88
	v_mul_f32_e32 v88, v93, v93
	v_fma_f32 v92, -v92, v88, 0.5
	v_fma_f32 v88, v93, v92, v93
	v_mul_f32_e32 v88, v149, v88
	v_pk_mul_f32 v[78:79], v[78:79], v[88:89] op_sel_hi:[1,0]
	v_pk_mul_f32 v[76:77], v[76:77], v[88:89] op_sel_hi:[1,0]
	v_pk_mul_f32 v[74:75], v[74:75], v[88:89] op_sel_hi:[1,0]
	v_pk_mul_f32 v[72:73], v[72:73], v[88:89] op_sel_hi:[1,0]
	v_pk_mul_f32 v[70:71], v[70:71], v[88:89] op_sel_hi:[1,0]
	v_pk_mul_f32 v[68:69], v[68:69], v[88:89] op_sel_hi:[1,0]
	v_pk_mul_f32 v[90:91], v[66:67], v[88:89] op_sel_hi:[1,0]
	v_pk_mul_f32 v[88:89], v[64:65], v[88:89] op_sel_hi:[1,0]
	v_cvt_pk_bf16_f32 v64, v76, v77
	v_cvt_pk_bf16_f32 v65, v78, v79
	v_cvt_pk_bf16_f32 v66, v72, v73
	v_cvt_pk_bf16_f32 v67, v74, v75
	global_store_dwordx4 v[82:83], v[64:67], off
	s_nop 1
	v_cvt_pk_bf16_f32 v64, v68, v69
	v_cvt_pk_bf16_f32 v65, v70, v71
	v_cvt_pk_bf16_f32 v66, v88, v89
	v_cvt_pk_bf16_f32 v67, v90, v91
	global_store_dwordx4 v[86:87], v[64:67], off
	global_load_dwordx4 v[64:67], v[84:85], off
	s_waitcnt vmcnt(0)
	v_mov_b32_e32 v68, v65
	v_mov_b32_e32 v69, v66
	v_mov_b32_e32 v65, v67
	v_pk_add_f32 v[64:65], v[68:69], v[64:65]
	v_lshlrev_b64 v[66:67], 7, v[80:81]
	v_add_f32_e32 v64, v64, v65
	ds_bpermute_b32 v65, v159, v64
	v_lshl_add_u64 v[66:67], s[26:27], 0, v[66:67]
	v_lshl_add_u64 v[66:67], v[66:67], 0, v[136:137]
	s_waitcnt lgkmcnt(0)
	v_add_f32_e32 v70, v64, v65
	ds_bpermute_b32 v71, v160, v70
	v_add_u32_e32 v64, 0x90, v148
	v_ashrrev_i32_e32 v65, 31, v64
	v_lshlrev_b64 v[68:69], 6, v[64:65]
	v_lshl_add_u64 v[68:69], v[138:139], 0, v[68:69]
	s_waitcnt lgkmcnt(0)
	v_add_f32_e32 v70, v70, v71
	v_fmamk_f32 v70, v70, 0x3a800000, v156
	v_mov_b32_e32 v72, v70
	v_add_co_u32_e32 v70, vcc, s49, v66
	s_nop 1
	v_addc_co_u32_e32 v71, vcc, 0, v67, vcc
	v_rsq_f32_e32 v77, v72
	v_mul_f32_e32 v76, 0.5, v72
	v_mul_f32_e32 v72, v77, v77
	v_fma_f32 v76, -v76, v72, 0.5
	v_fma_f32 v72, v77, v76, v77
	v_mul_f32_e32 v72, v149, v72
	v_pk_mul_f32 v[62:63], v[62:63], v[72:73] op_sel_hi:[1,0]
	v_pk_mul_f32 v[60:61], v[60:61], v[72:73] op_sel_hi:[1,0]
	v_pk_mul_f32 v[58:59], v[58:59], v[72:73] op_sel_hi:[1,0]
	v_pk_mul_f32 v[56:57], v[56:57], v[72:73] op_sel_hi:[1,0]
	v_pk_mul_f32 v[54:55], v[54:55], v[72:73] op_sel_hi:[1,0]
	v_pk_mul_f32 v[52:53], v[52:53], v[72:73] op_sel_hi:[1,0]
	v_pk_mul_f32 v[74:75], v[50:51], v[72:73] op_sel_hi:[1,0]
	v_pk_mul_f32 v[72:73], v[48:49], v[72:73] op_sel_hi:[1,0]
	v_cvt_pk_bf16_f32 v48, v60, v61
	v_cvt_pk_bf16_f32 v49, v62, v63
	v_cvt_pk_bf16_f32 v50, v56, v57
	v_cvt_pk_bf16_f32 v51, v58, v59
	global_store_dwordx4 v[66:67], v[48:51], off
	s_nop 1
	v_cvt_pk_bf16_f32 v48, v52, v53
	v_cvt_pk_bf16_f32 v49, v54, v55
	v_cvt_pk_bf16_f32 v50, v72, v73
	v_cvt_pk_bf16_f32 v51, v74, v75
	global_store_dwordx4 v[70:71], v[48:51], off
	global_load_dwordx4 v[48:51], v[68:69], off
	s_waitcnt vmcnt(0)
	v_mov_b32_e32 v52, v49
	v_mov_b32_e32 v53, v50
	v_mov_b32_e32 v49, v51
	v_pk_add_f32 v[48:49], v[52:53], v[48:49]
	v_lshlrev_b64 v[50:51], 7, v[64:65]
	v_add_f32_e32 v48, v48, v49
	ds_bpermute_b32 v49, v159, v48
	v_lshl_add_u64 v[50:51], s[26:27], 0, v[50:51]
	v_lshl_add_u64 v[50:51], v[50:51], 0, v[136:137]
	s_waitcnt lgkmcnt(0)
	v_add_f32_e32 v54, v48, v49
	ds_bpermute_b32 v55, v160, v54
	v_add_u32_e32 v48, 0xa0, v148
	v_ashrrev_i32_e32 v49, 31, v48
	v_lshlrev_b64 v[52:53], 6, v[48:49]
	v_lshl_add_u64 v[52:53], v[138:139], 0, v[52:53]
	s_waitcnt lgkmcnt(0)
	v_add_f32_e32 v54, v54, v55
	v_fmamk_f32 v54, v54, 0x3a800000, v156
	v_mov_b32_e32 v56, v54
	v_add_co_u32_e32 v54, vcc, s49, v50
	s_nop 1
	v_addc_co_u32_e32 v55, vcc, 0, v51, vcc
	v_rsq_f32_e32 v61, v56
	v_mul_f32_e32 v60, 0.5, v56
	v_mul_f32_e32 v56, v61, v61
	v_fma_f32 v60, -v60, v56, 0.5
	v_fma_f32 v56, v61, v60, v61
	v_mul_f32_e32 v56, v149, v56
	v_pk_mul_f32 v[46:47], v[46:47], v[56:57] op_sel_hi:[1,0]
	v_pk_mul_f32 v[44:45], v[44:45], v[56:57] op_sel_hi:[1,0]
	v_pk_mul_f32 v[42:43], v[42:43], v[56:57] op_sel_hi:[1,0]
	v_pk_mul_f32 v[40:41], v[40:41], v[56:57] op_sel_hi:[1,0]
	v_pk_mul_f32 v[38:39], v[38:39], v[56:57] op_sel_hi:[1,0]
	v_pk_mul_f32 v[36:37], v[36:37], v[56:57] op_sel_hi:[1,0]
	v_pk_mul_f32 v[58:59], v[34:35], v[56:57] op_sel_hi:[1,0]
	v_pk_mul_f32 v[56:57], v[32:33], v[56:57] op_sel_hi:[1,0]
	v_cvt_pk_bf16_f32 v32, v44, v45
	v_cvt_pk_bf16_f32 v33, v46, v47
	v_cvt_pk_bf16_f32 v34, v40, v41
	v_cvt_pk_bf16_f32 v35, v42, v43
	global_store_dwordx4 v[50:51], v[32:35], off
	s_nop 1
	v_cvt_pk_bf16_f32 v32, v36, v37
	v_cvt_pk_bf16_f32 v33, v38, v39
	v_cvt_pk_bf16_f32 v34, v56, v57
	v_cvt_pk_bf16_f32 v35, v58, v59
	global_store_dwordx4 v[54:55], v[32:35], off
	global_load_dwordx4 v[32:35], v[52:53], off
	s_waitcnt vmcnt(0)
	v_mov_b32_e32 v36, v33
	v_mov_b32_e32 v37, v34
	v_mov_b32_e32 v33, v35
	v_pk_add_f32 v[32:33], v[36:37], v[32:33]
	v_lshlrev_b64 v[34:35], 7, v[48:49]
	v_add_f32_e32 v32, v32, v33
	ds_bpermute_b32 v33, v159, v32
	v_lshl_add_u64 v[34:35], s[26:27], 0, v[34:35]
	v_lshl_add_u64 v[34:35], v[34:35], 0, v[136:137]
	s_waitcnt lgkmcnt(0)
	v_add_f32_e32 v38, v32, v33
	ds_bpermute_b32 v39, v160, v38
	v_add_u32_e32 v32, 0xb0, v148
	v_ashrrev_i32_e32 v33, 31, v32
	v_lshlrev_b64 v[36:37], 6, v[32:33]
	v_lshl_add_u64 v[36:37], v[138:139], 0, v[36:37]
	s_waitcnt lgkmcnt(0)
	v_add_f32_e32 v38, v38, v39
	v_fmamk_f32 v38, v38, 0x3a800000, v156
	v_mov_b32_e32 v40, v38
	v_add_co_u32_e32 v38, vcc, s49, v34
	s_nop 1
	v_addc_co_u32_e32 v39, vcc, 0, v35, vcc
	v_rsq_f32_e32 v45, v40
	v_mul_f32_e32 v44, 0.5, v40
	v_mul_f32_e32 v40, v45, v45
	v_fma_f32 v44, -v44, v40, 0.5
	v_fma_f32 v40, v45, v44, v45
	v_mul_f32_e32 v40, v149, v40
	v_pk_mul_f32 v[30:31], v[30:31], v[40:41] op_sel_hi:[1,0]
	v_pk_mul_f32 v[28:29], v[28:29], v[40:41] op_sel_hi:[1,0]
	v_pk_mul_f32 v[26:27], v[26:27], v[40:41] op_sel_hi:[1,0]
	v_pk_mul_f32 v[24:25], v[24:25], v[40:41] op_sel_hi:[1,0]
	v_pk_mul_f32 v[22:23], v[22:23], v[40:41] op_sel_hi:[1,0]
	v_pk_mul_f32 v[20:21], v[20:21], v[40:41] op_sel_hi:[1,0]
	v_pk_mul_f32 v[42:43], v[18:19], v[40:41] op_sel_hi:[1,0]
	v_pk_mul_f32 v[40:41], v[16:17], v[40:41] op_sel_hi:[1,0]
	v_cvt_pk_bf16_f32 v16, v28, v29
	v_cvt_pk_bf16_f32 v17, v30, v31
	v_cvt_pk_bf16_f32 v18, v24, v25
	v_cvt_pk_bf16_f32 v19, v26, v27
	global_store_dwordx4 v[34:35], v[16:19], off
	s_nop 1
	v_cvt_pk_bf16_f32 v16, v20, v21
	v_cvt_pk_bf16_f32 v17, v22, v23
	v_cvt_pk_bf16_f32 v18, v40, v41
	v_cvt_pk_bf16_f32 v19, v42, v43
	global_store_dwordx4 v[38:39], v[16:19], off
	global_load_dwordx4 v[16:19], v[36:37], off
	s_waitcnt vmcnt(0)
	v_mov_b32_e32 v20, v17
	v_mov_b32_e32 v21, v18
	v_mov_b32_e32 v17, v19
	v_pk_add_f32 v[16:17], v[20:21], v[16:17]
	s_nop 0
	v_add_f32_e32 v16, v16, v17
	ds_bpermute_b32 v17, v159, v16
	s_waitcnt lgkmcnt(0)
	v_add_f32_e32 v16, v16, v17
	ds_bpermute_b32 v17, v160, v16
	s_waitcnt lgkmcnt(0)
	v_add_f32_e32 v16, v16, v17
	v_fmamk_f32 v16, v16, 0x3a800000, v156
	v_mov_b32_e32 v18, v16
	v_lshlrev_b64 v[16:17], 7, v[32:33]
	v_lshl_add_u64 v[16:17], s[26:27], 0, v[16:17]
	v_lshl_add_u64 v[16:17], v[16:17], 0, v[136:137]
	v_mov_b32_e32 v19, v18
	v_add_co_u32_e32 v18, vcc, 64, v16
	v_rsq_f32_e32 v23, v19
	v_mul_f32_e32 v22, 0.5, v19
	v_mul_f32_e32 v20, v23, v23
	v_fma_f32 v22, -v22, v20, 0.5
	v_fma_f32 v20, v23, v22, v23
	s_nop 0
	v_addc_co_u32_e32 v19, vcc, 0, v17, vcc
	v_mul_f32_e32 v20, v149, v20
	s_andn2_b64 vcc, exec, s[0:1]
	v_pk_mul_f32 v[14:15], v[14:15], v[20:21] op_sel_hi:[1,0]
	v_pk_mul_f32 v[12:13], v[12:13], v[20:21] op_sel_hi:[1,0]
	v_pk_mul_f32 v[10:11], v[10:11], v[20:21] op_sel_hi:[1,0]
	v_pk_mul_f32 v[8:9], v[8:9], v[20:21] op_sel_hi:[1,0]
	v_pk_mul_f32 v[6:7], v[6:7], v[20:21] op_sel_hi:[1,0]
	v_pk_mul_f32 v[4:5], v[4:5], v[20:21] op_sel_hi:[1,0]
	v_pk_mul_f32 v[22:23], v[2:3], v[20:21] op_sel_hi:[1,0]
	v_pk_mul_f32 v[20:21], v[0:1], v[20:21] op_sel_hi:[1,0]
	v_cvt_pk_bf16_f32 v0, v12, v13
	v_cvt_pk_bf16_f32 v1, v14, v15
	v_cvt_pk_bf16_f32 v2, v8, v9
	v_cvt_pk_bf16_f32 v3, v10, v11
	s_mov_b64 s[0:1], -1
	global_store_dwordx4 v[16:17], v[0:3], off
	s_nop 1
	v_cvt_pk_bf16_f32 v0, v4, v5
	v_cvt_pk_bf16_f32 v1, v6, v7
	v_cvt_pk_bf16_f32 v2, v20, v21
	v_cvt_pk_bf16_f32 v3, v22, v23
	global_store_dwordx4 v[18:19], v[0:3], off
	s_cbranch_vccnz .LBB0_932
	s_andn2_b64 vcc, exec, s[8:9]
	s_cbranch_vccnz .LBB0_931
	s_barrier
	s_branch .LBB0_931
